# grid barrier 1 removed: P1 waits only for mod items 0..63 (write-through stores + 8 replicated counters); shared barrier body counts from zero
# baseline (speedup 1.0000x reference)
; __device__ __forceinline__ void mod_phase(const Params& p, const bf16_t* __restrict__ Sb, float* smem) {
;     ...
;         for (int idx = tid; idx < 9 * 64; idx += 512) { const int bt = idx >> 6, l = idx & 63; f32x4 sa = red[bt * 64 + l], sb = red[(9 + bt) * 64 + l];
; #pragma unroll
;             for (int w2 = 1; w2 < 4; ++w2) { sa += red[(w2 * 18 + bt) * 64 + l]; sb += red[(w2 * 18 + 9 + bt) * 64 + l]; }
;             const int b = bt * 16 + (l & 15), j = col0 + (l >> 4) * 8;
;             if (b < NB) { float* mp = mod + (size_t)b * NMOD + j;
;                 *(f32x4*)mp = (f32x4){sa[0], sb[0], sa[1], sb[1]} + *(const f32x4*)(p.b_ada + j);
;                 *(f32x4*)(mp + 4) = (f32x4){sa[2], sb[2], sa[3], sb[3]} + *(const f32x4*)(p.b_ada + j + 4); } }
.LBB0_79:
	v_ashrrev_i32_e32 v3, 6, v1
	v_lshl_or_b32 v2, v3, 4, v152
	v_cmp_gt_i32_e32 vcc, s52, v2
	s_and_saveexec_b64 s[26:27], vcc
	s_cbranch_execz .LBB0_78
	v_lshrrev_b32_e32 v4, 1, v1
	v_and_or_b32 v4, v4, 24, s10
	v_ashrrev_i32_e32 v5, 31, v4
	v_lshlrev_b64 v[40:41], 2, v[4:5]
	v_lshl_add_u64 v[42:43], s[50:51], 0, v[40:41]
	global_load_dwordx4 v[4:7], v[42:43], off
	v_and_b32_e32 v12, 0xfffffc0, v1
	v_lshl_add_u32 v3, v3, 10, v140
	ds_read_b128 v[8:11], v0
	v_lshl_add_u32 v32, v12, 4, v140
	ds_read_b128 v[12:15], v3 offset:27648
	ds_read_b128 v[16:19], v3 offset:64512
	ds_read_b128 v[20:23], v3 offset:18432
	ds_read_b128 v[24:27], v3 offset:46080
	ds_read_b128 v[28:31], v3 offset:55296
	ds_read_b128 v[32:35], v32 offset:9216
	ds_read_b128 v[36:39], v3 offset:36864
	v_mov_b64_e32 v[44:45], s[16:17]
	v_mad_i64_i32 v[2:3], s[60:61], v2, s12, v[44:45]
	v_lshl_add_u64 v[40:41], v[2:3], 0, v[40:41]
	s_waitcnt lgkmcnt(4)
	v_pk_add_f32 v[2:3], v[8:9], v[20:21]
	s_waitcnt lgkmcnt(1)
	v_pk_add_f32 v[8:9], v[32:33], v[12:13]
	s_waitcnt lgkmcnt(0)
	v_pk_add_f32 v[2:3], v[2:3], v[36:37]
	v_pk_add_f32 v[8:9], v[8:9], v[24:25]
	v_pk_add_f32 v[2:3], v[2:3], v[28:29]
	v_pk_add_f32 v[8:9], v[8:9], v[16:17]
	v_mov_b32_e32 v12, v2
	v_mov_b32_e32 v13, v8
	v_mov_b32_e32 v8, v3
	s_waitcnt vmcnt(0)
	v_pk_add_f32 v[2:3], v[4:5], v[12:13]
	v_pk_add_f32 v[4:5], v[6:7], v[8:9]
	global_store_dwordx4 v[40:41], v[2:5], off sc1
	global_load_dwordx4 v[2:5], v[42:43], off offset:16
	v_pk_add_f32 v[6:7], v[10:11], v[22:23]
	v_pk_add_f32 v[8:9], v[34:35], v[14:15]
	v_pk_add_f32 v[6:7], v[6:7], v[38:39]
	v_pk_add_f32 v[8:9], v[8:9], v[26:27]
	v_pk_add_f32 v[6:7], v[6:7], v[30:31]
	v_pk_add_f32 v[8:9], v[8:9], v[18:19]
	v_mov_b32_e32 v10, v6
	v_mov_b32_e32 v11, v8
	v_mov_b32_e32 v8, v7
	s_waitcnt vmcnt(0)
	v_pk_add_f32 v[2:3], v[10:11], v[2:3]
	v_pk_add_f32 v[4:5], v[8:9], v[4:5]
	global_store_dwordx4 v[40:41], v[2:5], off offset:16 sc1
	s_branch .LBB0_78

; __device__ __forceinline__ unsigned cvt_pk_bf16(float lo, float hi) { unsigned r; asm("v_cvt_pk_bf16_f32 %0, %1, %2" : "=v"(r) : "v"(lo), "v"(hi)); return r; }
; __device__ __forceinline__ int fresh_tid() { int t = threadIdx.x; asm volatile("" : "+v"(t)); return t; }
; __device__ __forceinline__ unsigned xb_add(unsigned* p, unsigned v) { return __hip_atomic_fetch_add(p, v, __ATOMIC_RELAXED, __HIP_MEMORY_SCOPE_AGENT); }
; __device__ __forceinline__ void spin_until(unsigned* p, unsigned need) { unsigned sp = 0; while (xb_ld(p) < need) { __builtin_amdgcn_s_sleep(1); if (++sp > (1u << 20)) break; } }
; __global__ __launch_bounds__(512, 2) void fwd_megakernel(Params p) {
;     ...
;       if (bid < 144 * DM / 8 / 512) { asm volatile("s_waitcnt vmcnt(0)" ::: "memory"); __syncthreads();
;           if (fresh_tid() == 0) { __builtin_amdgcn_fence(__ATOMIC_RELEASE, "agent"); asm volatile("s_waitcnt vmcnt(0)" ::: "memory"); xb_add(cs, 1u); } }
;       bf16_t* Wt = (bf16_t*)(p.ws + WS_WTRIL);
;       for (int i = bid * 512 + tid; i < 8 * 128 * 128; i += G * 512) { const int t = (i >> 7) & 127, s = i & 127; Wt[i] = (bf16_t)(cvt_pk_bf16(s <= t ? p.w_s[i] : 0.f, 0.f) & 0xffffu); }
;       { const int nslot = (bid < NMOD / 32) ? 1 : 3, slot0 = (bid < NMOD / 32) ? bid : NMOD / 32 + 3 * (bid - NMOD / 32), nslots = NMOD / 32 + 3 * (G - NMOD / 32);
; #pragma unroll 1
;         for (int j = 0; j < nslot; ++j) { int ctr = 0;
;           transpose_cvt<true, true>(p.w_in, WinT, DM, DIN, (float*)shm, ctr, slot0 + j, nslots);
;           transpose_cvt<false, true>(p.w_out, WoutT, DM, DM, (float*)shm, ctr, slot0 + j, nslots);
;           transpose_cvt<false, true>(p.w_ff2, Wff2T, DFF, DM, (float*)shm, ctr, slot0 + j, nslots);
;           transpose_cvt<false, true>(p.w_ff1, Wff1T, DM, DFF, (float*)shm, ctr, slot0 + j, nslots); } }
;       if (p.use_cg_sync) grid.sync();
;       asm volatile("s_waitcnt vmcnt(0)" ::: "memory"); __syncthreads();
;       if (fresh_tid() == 0) { asm volatile("buffer_inv sc1" ::: "memory"); spin_until(cs, 144 * DM / 8 / 512); asm volatile("s_waitcnt vmcnt(0)" ::: "memory"); }
;       __syncthreads();
;       mod_phase(p, Sb, (float*)shm); }
;     xcd_barrier(xb);
.LBB0_97:
	s_cmp_gt_u32 s2, 63
	s_cbranch_scc1 .LBB0_133
	s_add_u32 s14, s58, 0xc944300
	s_addc_u32 s15, s59, 0
	s_mov_b64 exec, 0xff
	v_mbcnt_lo_u32_b32 v3, -1, 0
	v_lshlrev_b32_e32 v3, 8, v3
	v_mov_b32_e32 v4, 1
	global_atomic_add v3, v4, s[14:15]
	s_mov_b64 exec, 1
.LBB0_133:
	s_or_b64 exec, exec, s[0:1]
	v_readlane_b32 s4, v240, 0
	v_readlane_b32 s5, v240, 1
	s_and_b64 s[4:5], exec, s[4:5]
	s_cbranch_scc0 .Lmw_done
	s_add_u32 s8, s58, 0xc944300
	s_addc_u32 s9, s59, 0
	s_and_b32 s10, s2, 7
	s_lshl_b32 s10, s10, 8
	v_mov_b32_e32 v0, s10
	s_mov_b32 s10, 0
.Lmw_loop:
	global_load_dword v1, v0, s[8:9] sc1
	s_waitcnt vmcnt(0)
	s_nop 0
	v_readfirstlane_b32 s11, v1
	s_cmp_gt_u32 s11, 63
	s_cbranch_scc1 .Lmw_inv
	s_sleep 1
	s_add_i32 s10, s10, 1
	s_cmp_lt_u32 s10, 0x40000
	s_cbranch_scc1 .Lmw_loop

; __device__ __forceinline__ int fresh_tid() { int t = threadIdx.x; asm volatile("" : "+v"(t)); return t; }
; __device__ __forceinline__ void st_bf16x8(bf16_t* p, const f32x4 a, const f32x4 b) { uint4 o; o.x = cvt_pk_bf16(a[0], a[1]); o.y = cvt_pk_bf16(a[2], a[3]); o.z = cvt_pk_bf16(b[0], b[1]); o.w = cvt_pk_bf16(b[2], b[3]); *(uint4*)p = o; }
; __device__ __forceinline__ void p1_prompt_rows(const Params& p) {
;     const int tid = fresh_tid(), lane = tid & 63, gw = blockIdx.x * 8 + (tid >> 6);
;     const float* mb = (const float*)(p.ws + WS_MOD) + (size_t)(gw >> 8) * NMOD; bf16_t* H = (bf16_t*)(p.ws + WS_H);
;     f32x4 gs[4], sh[4];
; #pragma unroll
;     for (int i = 0; i < 4; ++i) { const int c = (i >> 1) * 512 + lane * 8 + (i & 1) * 4; gs[i] = *(const f32x4*)(p.g_mix + c) * (*(const f32x4*)(mb + 1024 + c) + 1.f); sh[i] = *(const f32x4*)(mb + c); }
; #pragma unroll
;     for (int trip = 0; trip < 2; ++trip) { const int rowb = gw * 8 + trip * 4;
;         f32x4 v[4][4];
; #pragma unroll
;         for (int q = 0; q < 4; ++q)
; #pragma unroll
;             for (int i = 0; i < 4; ++i) v[q][i] = *(const f32x4*)(p.x_prompt + (size_t)(rowb + q) * DM + (i >> 1) * 512 + lane * 8 + (i & 1) * 4);
;         __builtin_amdgcn_sched_barrier(0);
; #pragma unroll
;         for (int q = 0; q < 4; ++q) { float ss = 0.f;
; #pragma unroll
;             for (int i = 0; i < 4; ++i) ss += v[q][i][0] * v[q][i][0] + v[q][i][1] * v[q][i][1] + v[q][i][2] * v[q][i][2] + v[q][i][3] * v[q][i][3];
; #pragma unroll
;             for (int o = 1; o < 64; o <<= 1) ss += __shfl_xor(ss, o);
;             const float rs = rsqrtf(ss * (1.f / DM) + EPS);
; #pragma unroll
;             for (int h = 0; h < 2; ++h) st_bf16x8(H + (size_t)(rowb + q) * DM + h * 512 + lane * 8, v[q][2 * h] * rs * gs[2 * h] + sh[2 * h], v[q][2 * h + 1] * rs * gs[2 * h + 1] + sh[2 * h + 1]); }
.Lmw_done:
	s_add_u32 s26, s58, 0x1a70000
	v_mov_b32_e32 v2, v224
	s_addc_u32 s27, s59, 0
	s_waitcnt lgkmcnt(0)
	s_barrier
	s_lshl_b32 s95, s2, 3
	s_mov_b64 s[10:11], 0x1000
	v_ashrrev_i32_e32 v0, 6, v2
	v_add_u32_e32 v20, s95, v0
	v_lshrrev_b32_e32 v0, 8, v20
	v_lshlrev_b32_e32 v2, 3, v2
	v_mul_hi_i32_i24_e32 v1, 0x6000, v0
	v_mul_i32_i24_e32 v0, 0x6000, v0
	v_and_b32_e32 v126, 0x1f8, v2
	v_lshl_add_u64 v[0:1], s[16:17], 0, v[0:1]
	v_lshlrev_b32_e32 v80, 2, v126
	v_mov_b32_e32 v81, 0
	v_lshl_add_u64 v[4:5], v[0:1], 0, s[10:11]
	v_or_b32_e32 v6, 0x800, v80
	v_mov_b32_e32 v7, v81
	v_lshlrev_b32_e32 v102, 3, v20
	v_lshl_add_u64 v[2:3], v[4:5], 0, v[80:81]
	v_lshl_add_u64 v[16:17], v[0:1], 0, v[80:81]
	v_lshl_add_u64 v[18:19], v[4:5], 0, v[6:7]
	v_ashrrev_i32_e32 v103, 31, v102
	global_load_dwordx4 v[82:85], v80, s[46:47] offset:16
	global_load_dwordx4 v[86:89], v80, s[46:47]
	global_load_dwordx4 v[90:93], v[2:3], off offset:16
	global_load_dwordx4 v[94:97], v[2:3], off
	s_nop 0
	global_load_dwordx4 v[0:3], v[16:17], off offset:16
	global_load_dwordx4 v[8:11], v[16:17], off
	global_load_dwordx4 v[112:115], v80, s[46:47] offset:2064
	global_load_dwordx4 v[116:119], v80, s[46:47] offset:2048
	global_load_dwordx4 v[98:101], v[18:19], off offset:16
	global_load_dwordx4 v[120:123], v[18:19], off
	global_load_dwordx4 v[4:7], v[16:17], off offset:2064
	global_load_dwordx4 v[12:15], v[16:17], off offset:2048
	v_lshl_add_u64 v[104:105], s[36:37], 0, v[80:81]
	v_lshlrev_b64 v[16:17], 12, v[102:103]
	v_or_b32_e32 v110, 1, v102
	v_lshl_add_u64 v[16:17], v[104:105], 0, v[16:17]
	v_ashrrev_i32_e32 v111, 31, v110
	global_load_dwordx4 v[76:79], v[16:17], off nt
	global_load_dwordx4 v[72:75], v[16:17], off offset:16 nt
	global_load_dwordx4 v[68:71], v[16:17], off offset:2048 nt
	global_load_dwordx4 v[64:67], v[16:17], off offset:2064 nt
	v_lshlrev_b64 v[16:17], 12, v[110:111]
	v_or_b32_e32 v108, 2, v102
	v_lshl_add_u64 v[16:17], v[104:105], 0, v[16:17]
	v_ashrrev_i32_e32 v109, 31, v108
	global_load_dwordx4 v[60:63], v[16:17], off nt
	global_load_dwordx4 v[56:59], v[16:17], off offset:16 nt
	global_load_dwordx4 v[52:55], v[16:17], off offset:2048 nt
	global_load_dwordx4 v[48:51], v[16:17], off offset:2064 nt
	v_lshlrev_b64 v[16:17], 12, v[108:109]
	v_or_b32_e32 v106, 3, v102
	v_lshl_add_u64 v[16:17], v[104:105], 0, v[16:17]
	v_ashrrev_i32_e32 v107, 31, v106
	global_load_dwordx4 v[44:47], v[16:17], off nt
	global_load_dwordx4 v[40:43], v[16:17], off offset:16 nt
	global_load_dwordx4 v[36:39], v[16:17], off offset:2048 nt
	global_load_dwordx4 v[32:35], v[16:17], off offset:2064 nt
	v_lshlrev_b64 v[16:17], 12, v[106:107]
	v_lshl_add_u64 v[124:125], v[104:105], 0, v[16:17]
	global_load_dwordx4 v[28:31], v[124:125], off nt
	global_load_dwordx4 v[24:27], v[124:125], off offset:16 nt
	global_load_dwordx4 v[20:23], v[124:125], off offset:2048 nt
	global_load_dwordx4 v[16:19], v[124:125], off offset:2064 nt
	v_mbcnt_lo_u32_b32 v80, -1, 0
	v_mbcnt_hi_u32_b32 v80, -1, v80
	s_movk_i32 s12, 0x4000
	s_movk_i32 s13, 0x6000
	s_lshl_b32 s94, s34, 3
	s_add_i32 s97, s95, 0x4000
	s_waitcnt vmcnt(19)
	v_pk_add_f32 v[124:125], v[98:99], 1.0 op_sel_hi:[1,0]
	v_pk_add_f32 v[94:95], v[94:95], 1.0 op_sel_hi:[1,0]
	v_pk_add_f32 v[90:91], v[90:91], 1.0 op_sel_hi:[1,0]
	s_waitcnt vmcnt(18)
	v_pk_add_f32 v[120:121], v[120:121], 1.0 op_sel_hi:[1,0]
	v_pk_mul_f32 v[98:99], v[86:87], v[94:95]
	v_pk_mul_f32 v[94:95], v[82:83], v[90:91]
	v_and_b32_e32 v82, 64, v80
	v_pk_add_f32 v[96:97], v[96:97], 1.0 op_sel_hi:[1,0]
	v_pk_add_f32 v[92:93], v[92:93], 1.0 op_sel_hi:[1,0]
	v_pk_add_f32 v[122:123], v[122:123], 1.0 op_sel_hi:[1,0]
	v_pk_add_f32 v[100:101], v[100:101], 1.0 op_sel_hi:[1,0]
	v_pk_mul_f32 v[90:91], v[116:117], v[120:121]
	v_add_u32_e32 v116, 64, v82
	v_lshlrev_b32_e32 v82, 1, v126
	v_mov_b32_e32 v83, v81
	v_pk_mul_f32 v[96:97], v[88:89], v[96:97]
	v_pk_mul_f32 v[92:93], v[84:85], v[92:93]
	v_pk_mul_f32 v[88:89], v[118:119], v[122:123]
	v_pk_mul_f32 v[84:85], v[114:115], v[100:101]
	v_pk_mul_f32 v[86:87], v[112:113], v[124:125]
	v_lshl_add_u64 v[100:101], s[26:27], 0, v[82:83]
	s_waitcnt vmcnt(15)
	v_mov_b32_e32 v112, v77
	s_waitcnt vmcnt(14)
	v_mov_b32_e32 v113, v73
	v_mov_b32_e32 v82, v76
	v_mov_b32_e32 v83, v72
	v_pk_mul_f32 v[112:113], v[112:113], v[112:113]
	s_waitcnt vmcnt(13)
	v_mov_b32_e32 v114, v69
	v_pk_fma_f32 v[82:83], v[82:83], v[82:83], v[112:113]
	v_mov_b32_e32 v112, v78
	v_mov_b32_e32 v113, v74
	v_pk_fma_f32 v[82:83], v[112:113], v[112:113], v[82:83]
	v_mov_b32_e32 v112, v79
	v_mov_b32_e32 v113, v75
	s_waitcnt vmcnt(12)
	v_mov_b32_e32 v115, v65
	v_pk_fma_f32 v[82:83], v[112:113], v[112:113], v[82:83]
	v_mov_b32_e32 v112, v68
	v_mov_b32_e32 v113, v64
	v_pk_mul_f32 v[114:115], v[114:115], v[114:115]
	v_add_f32_e32 v82, v82, v83
	v_pk_fma_f32 v[112:113], v[112:113], v[112:113], v[114:115]
	v_mov_b32_e32 v114, v70
	v_mov_b32_e32 v115, v66
	v_pk_fma_f32 v[112:113], v[114:115], v[114:115], v[112:113]
	v_mov_b32_e32 v114, v71
	v_mov_b32_e32 v115, v67
	v_xor_b32_e32 v83, 1, v80
	v_pk_fma_f32 v[112:113], v[114:115], v[114:115], v[112:113]
	v_cmp_lt_i32_e32 vcc, v83, v116
	v_add_f32_e32 v82, v82, v112
	v_add_f32_e32 v82, v82, v113
	v_cndmask_b32_e32 v83, v80, v83, vcc
	v_lshlrev_b32_e32 v225, 2, v83
	ds_bpermute_b32 v83, v225, v82
	s_mov_b32 s15, 0x800000
	s_waitcnt vmcnt(10)
	v_mov_b32_e32 v117, v57
	v_mov_b32_e32 v114, v60
	v_mov_b32_e32 v115, v56
	s_waitcnt lgkmcnt(0)
	v_add_f32_e32 v82, v82, v83
	v_xor_b32_e32 v83, 2, v80
	v_cmp_lt_i32_e32 vcc, v83, v116
	s_waitcnt vmcnt(9)
	v_mov_b32_e32 v118, v53
	s_waitcnt vmcnt(8)
; __device__ __forceinline__ void st_bf16x8(bf16_t* p, const f32x4 a, const f32x4 b) { uint4 o; o.x = cvt_pk_bf16(a[0], a[1]); o.y = cvt_pk_bf16(a[2], a[3]); o.z = cvt_pk_bf16(b[0], b[1]); o.w = cvt_pk_bf16(b[2], b[3]); *(uint4*)p = o; }
; __device__ __forceinline__ void p1_prompt_rows(const Params& p) {
;     ...
; #pragma unroll
;         for (int q = 0; q < 4; ++q) { float ss = 0.f;
; #pragma unroll
;             for (int i = 0; i < 4; ++i) ss += v[q][i][0] * v[q][i][0] + v[q][i][1] * v[q][i][1] + v[q][i][2] * v[q][i][2] + v[q][i][3] * v[q][i][3];
; #pragma unroll
;             for (int o = 1; o < 64; o <<= 1) ss += __shfl_xor(ss, o);
;             const float rs = rsqrtf(ss * (1.f / DM) + EPS);
; #pragma unroll
;             for (int h = 0; h < 2; ++h) st_bf16x8(H + (size_t)(rowb + q) * DM + h * 512 + lane * 8, v[q][2 * h] * rs * gs[2 * h] + sh[2 * h], v[q][2 * h + 1] * rs * gs[2 * h + 1] + sh[2 * h + 1]); }
	v_mov_b32_e32 v119, v49
	v_cndmask_b32_e32 v83, v80, v83, vcc
	v_lshlrev_b32_e32 v226, 2, v83
	ds_bpermute_b32 v83, v226, v82
	v_pk_mul_f32 v[118:119], v[118:119], v[118:119]
	v_lshlrev_b64 v[112:113], 11, v[102:103]
	v_lshl_add_u64 v[112:113], v[100:101], 0, v[112:113]
	s_mov_b32 s14, 0x3a800000
	s_waitcnt lgkmcnt(0)
	v_add_f32_e32 v82, v82, v83
	v_xor_b32_e32 v83, 4, v80
	v_cmp_lt_i32_e32 vcc, v83, v116
	s_nop 1
	v_cndmask_b32_e32 v83, v80, v83, vcc
	v_lshlrev_b32_e32 v227, 2, v83
	ds_bpermute_b32 v83, v227, v82
	s_waitcnt lgkmcnt(0)
	v_add_f32_e32 v82, v82, v83
	v_xor_b32_e32 v83, 8, v80
	v_cmp_lt_i32_e32 vcc, v83, v116
	s_nop 1
	v_cndmask_b32_e32 v83, v80, v83, vcc
	v_lshlrev_b32_e32 v228, 2, v83
	ds_bpermute_b32 v83, v228, v82
	s_waitcnt lgkmcnt(0)
	v_add_f32_e32 v82, v82, v83
	v_xor_b32_e32 v83, 16, v80
	v_cmp_lt_i32_e32 vcc, v83, v116
	s_nop 1
	v_cndmask_b32_e32 v83, v80, v83, vcc
	v_lshlrev_b32_e32 v229, 2, v83
	ds_bpermute_b32 v83, v229, v82
	s_waitcnt lgkmcnt(0)
	v_add_f32_e32 v82, v82, v83
	v_xor_b32_e32 v83, 32, v80
	v_cmp_lt_i32_e32 vcc, v83, v116
	v_mov_b32_e32 v116, v61
	v_pk_mul_f32 v[116:117], v[116:117], v[116:117]
	v_cndmask_b32_e32 v80, v80, v83, vcc
	v_lshlrev_b32_e32 v230, 2, v80
	ds_bpermute_b32 v80, v230, v82
	v_pk_fma_f32 v[114:115], v[114:115], v[114:115], v[116:117]
	v_mov_b32_e32 v116, v62
	v_mov_b32_e32 v117, v58
	v_pk_fma_f32 v[114:115], v[116:117], v[116:117], v[114:115]
	s_waitcnt lgkmcnt(0)
	v_add_f32_e32 v80, v82, v80
	v_mov_b32_e32 v82, 0x358637bd
	v_fmamk_f32 v80, v80, 0x3a800000, v82
	v_mul_f32_e32 v83, 0x4b800000, v80
	v_cmp_gt_f32_e32 vcc, s15, v80
	v_mov_b32_e32 v116, v63
	v_mov_b32_e32 v117, v59
	v_cndmask_b32_e32 v80, v80, v83, vcc
	v_rsq_f32_e32 v80, v80
	v_pk_fma_f32 v[114:115], v[116:117], v[116:117], v[114:115]
	v_mov_b32_e32 v116, v52
	v_mov_b32_e32 v117, v48
	v_pk_fma_f32 v[116:117], v[116:117], v[116:117], v[118:119]
	v_mov_b32_e32 v118, v54
	v_mov_b32_e32 v119, v50
	v_mul_f32_e32 v83, 0x45800000, v80
	v_pk_fma_f32 v[116:117], v[118:119], v[118:119], v[116:117]
	v_mov_b32_e32 v118, v55
	v_mov_b32_e32 v119, v51
	v_cndmask_b32_e32 v80, v80, v83, vcc
	v_pk_fma_f32 v[116:117], v[118:119], v[118:119], v[116:117]
	v_add_f32_e32 v83, v114, v115
	v_add_f32_e32 v83, v83, v116
	v_add_f32_e32 v83, v83, v117
	ds_bpermute_b32 v103, v225, v83
	v_pk_mul_f32 v[76:77], v[76:77], v[80:81] op_sel_hi:[1,0]
	v_pk_mul_f32 v[72:73], v[72:73], v[80:81] op_sel_hi:[1,0]
	v_pk_fma_f32 v[76:77], v[98:99], v[76:77], v[8:9]
	v_pk_mul_f32 v[74:75], v[74:75], v[80:81] op_sel_hi:[1,0]
	s_waitcnt lgkmcnt(0)
	v_add_f32_e32 v83, v83, v103
	ds_bpermute_b32 v103, v226, v83
	v_pk_fma_f32 v[114:115], v[92:93], v[74:75], v[2:3]
	v_pk_fma_f32 v[74:75], v[94:95], v[72:73], v[0:1]
	v_cvt_pk_bf16_f32 v72, v76, v77
	v_pk_mul_f32 v[78:79], v[78:79], v[80:81] op_sel_hi:[1,0]
	s_waitcnt lgkmcnt(0)
	v_add_f32_e32 v83, v83, v103
	ds_bpermute_b32 v103, v227, v83
	v_pk_fma_f32 v[78:79], v[96:97], v[78:79], v[10:11]
	v_cvt_pk_bf16_f32 v74, v74, v75
	v_cvt_pk_bf16_f32 v75, v114, v115
	v_pk_mul_f32 v[68:69], v[68:69], v[80:81] op_sel_hi:[1,0]
	s_waitcnt lgkmcnt(0)
	v_add_f32_e32 v76, v83, v103
	ds_bpermute_b32 v77, v228, v76
	v_cvt_pk_bf16_f32 v73, v78, v79
	global_store_dwordx4 v[112:113], v[72:75], off sc1
	v_pk_fma_f32 v[68:69], v[90:91], v[68:69], v[12:13]
	v_pk_mul_f32 v[64:65], v[64:65], v[80:81] op_sel_hi:[1,0]
	s_waitcnt lgkmcnt(0)
	v_add_f32_e32 v72, v76, v77
	ds_bpermute_b32 v73, v229, v72
	v_pk_mul_f32 v[66:67], v[66:67], v[80:81] op_sel_hi:[1,0]
	v_pk_mul_f32 v[70:71], v[70:71], v[80:81] op_sel_hi:[1,0]
	s_waitcnt lgkmcnt(0)
	v_add_f32_e32 v74, v72, v73
	ds_bpermute_b32 v75, v230, v74
	v_pk_fma_f32 v[72:73], v[84:85], v[66:67], v[6:7]
	v_pk_fma_f32 v[66:67], v[86:87], v[64:65], v[4:5]
	v_cvt_pk_bf16_f32 v64, v68, v69
	v_pk_fma_f32 v[70:71], v[88:89], v[70:71], v[14:15]
	s_waitcnt lgkmcnt(0)
	v_add_f32_e32 v68, v74, v75
	v_fmamk_f32 v68, v68, 0x3a800000, v82
	v_mul_f32_e32 v69, 0x4b800000, v68
	v_cmp_gt_f32_e32 vcc, s15, v68
	v_cvt_pk_bf16_f32 v65, v70, v71
	v_cvt_pk_bf16_f32 v66, v66, v67
	v_cvt_pk_bf16_f32 v67, v72, v73
	global_store_dwordx4 v[112:113], v[64:67], off offset:1024 sc1
	s_waitcnt vmcnt(9)
	v_mov_b32_e32 v70, v45
	v_cndmask_b32_e32 v68, v68, v69, vcc
	v_rsq_f32_e32 v68, v68
	s_waitcnt vmcnt(8)
	v_mov_b32_e32 v71, v41
	v_mov_b32_e32 v69, v40
	v_pk_mul_f32 v[70:71], v[70:71], v[70:71]
	v_mul_f32_e32 v64, 0x45800000, v68
	v_cndmask_b32_e32 v64, v68, v64, vcc
	v_mov_b32_e32 v68, v44
	v_pk_fma_f32 v[68:69], v[68:69], v[68:69], v[70:71]
	v_mov_b32_e32 v70, v46
	v_mov_b32_e32 v71, v42
	v_pk_fma_f32 v[68:69], v[70:71], v[70:71], v[68:69]
	v_mov_b32_e32 v70, v47
	v_mov_b32_e32 v71, v43
	s_waitcnt vmcnt(7)
	v_mov_b32_e32 v72, v37
	s_waitcnt vmcnt(6)
	v_mov_b32_e32 v73, v33
	v_pk_fma_f32 v[68:69], v[70:71], v[70:71], v[68:69]
	v_mov_b32_e32 v70, v36
	v_mov_b32_e32 v71, v32
	v_pk_mul_f32 v[72:73], v[72:73], v[72:73]
	v_add_f32_e32 v65, v68, v69
	v_pk_fma_f32 v[70:71], v[70:71], v[70:71], v[72:73]
	v_mov_b32_e32 v72, v38
	v_mov_b32_e32 v73, v34
	v_pk_fma_f32 v[70:71], v[72:73], v[72:73], v[70:71]
	v_mov_b32_e32 v72, v39
	v_mov_b32_e32 v73, v35
	v_pk_fma_f32 v[70:71], v[72:73], v[72:73], v[70:71]
	v_lshlrev_b64 v[66:67], 11, v[110:111]
	v_add_f32_e32 v65, v65, v70
	v_add_f32_e32 v65, v65, v71
	ds_bpermute_b32 v68, v225, v65
	v_pk_mul_f32 v[60:61], v[60:61], v[64:65] op_sel_hi:[1,0]
	v_pk_mul_f32 v[62:63], v[62:63], v[64:65] op_sel_hi:[1,0]
	v_pk_fma_f32 v[60:61], v[98:99], v[60:61], v[8:9]
	v_lshl_add_u64 v[66:67], v[100:101], 0, v[66:67]
	s_waitcnt lgkmcnt(0)
; __device__ __forceinline__ void st_bf16x8(bf16_t* p, const f32x4 a, const f32x4 b) { uint4 o; o.x = cvt_pk_bf16(a[0], a[1]); o.y = cvt_pk_bf16(a[2], a[3]); o.z = cvt_pk_bf16(b[0], b[1]); o.w = cvt_pk_bf16(b[2], b[3]); *(uint4*)p = o; }
; __device__ __forceinline__ void p1_prompt_rows(const Params& p) {
;     ...
; #pragma unroll
;         for (int q = 0; q < 4; ++q) { float ss = 0.f;
; #pragma unroll
;             for (int i = 0; i < 4; ++i) ss += v[q][i][0] * v[q][i][0] + v[q][i][1] * v[q][i][1] + v[q][i][2] * v[q][i][2] + v[q][i][3] * v[q][i][3];
; #pragma unroll
;             for (int o = 1; o < 64; o <<= 1) ss += __shfl_xor(ss, o);
;             const float rs = rsqrtf(ss * (1.f / DM) + EPS);
; #pragma unroll
;             for (int h = 0; h < 2; ++h) st_bf16x8(H + (size_t)(rowb + q) * DM + h * 512 + lane * 8, v[q][2 * h] * rs * gs[2 * h] + sh[2 * h], v[q][2 * h + 1] * rs * gs[2 * h + 1] + sh[2 * h + 1]); }
	v_add_f32_e32 v65, v65, v68
	ds_bpermute_b32 v70, v226, v65
	v_pk_mul_f32 v[56:57], v[56:57], v[64:65] op_sel_hi:[1,0]
	v_pk_mul_f32 v[58:59], v[58:59], v[64:65] op_sel_hi:[1,0]
	v_pk_fma_f32 v[62:63], v[96:97], v[62:63], v[10:11]
	v_pk_fma_f32 v[68:69], v[92:93], v[58:59], v[2:3]
	s_waitcnt lgkmcnt(0)
	v_add_f32_e32 v65, v65, v70
	ds_bpermute_b32 v70, v227, v65
	v_pk_fma_f32 v[58:59], v[94:95], v[56:57], v[0:1]
	v_cvt_pk_bf16_f32 v56, v60, v61
	v_cvt_pk_bf16_f32 v57, v62, v63
	v_pk_mul_f32 v[52:53], v[52:53], v[64:65] op_sel_hi:[1,0]
	s_waitcnt lgkmcnt(0)
	v_add_f32_e32 v60, v65, v70
	ds_bpermute_b32 v61, v228, v60
	v_cvt_pk_bf16_f32 v58, v58, v59
	v_cvt_pk_bf16_f32 v59, v68, v69
	global_store_dwordx4 v[66:67], v[56:59], off sc1
	v_pk_fma_f32 v[52:53], v[90:91], v[52:53], v[12:13]
	v_pk_mul_f32 v[48:49], v[48:49], v[64:65] op_sel_hi:[1,0]
	s_waitcnt lgkmcnt(0)
	v_add_f32_e32 v56, v60, v61
	ds_bpermute_b32 v57, v229, v56
	v_pk_mul_f32 v[50:51], v[50:51], v[64:65] op_sel_hi:[1,0]
	v_pk_mul_f32 v[54:55], v[54:55], v[64:65] op_sel_hi:[1,0]
	v_or_b32_e32 v110, 4, v102
	v_pk_fma_f32 v[54:55], v[88:89], v[54:55], v[14:15]
	s_waitcnt lgkmcnt(0)
	v_add_f32_e32 v58, v56, v57
	ds_bpermute_b32 v59, v230, v58
	v_pk_fma_f32 v[56:57], v[84:85], v[50:51], v[6:7]
	v_pk_fma_f32 v[50:51], v[86:87], v[48:49], v[4:5]
	v_cvt_pk_bf16_f32 v48, v52, v53
	v_cvt_pk_bf16_f32 v49, v54, v55
	s_waitcnt lgkmcnt(0)
	v_add_f32_e32 v52, v58, v59
	v_fmamk_f32 v52, v52, 0x3a800000, v82
	v_mul_f32_e32 v53, 0x4b800000, v52
	v_cmp_gt_f32_e32 vcc, s15, v52
	v_cvt_pk_bf16_f32 v50, v50, v51
	v_cvt_pk_bf16_f32 v51, v56, v57
	global_store_dwordx4 v[66:67], v[48:51], off offset:1024 sc1
	s_waitcnt vmcnt(7)
	v_mov_b32_e32 v54, v29
	v_cndmask_b32_e32 v52, v52, v53, vcc
	v_rsq_f32_e32 v52, v52
	s_waitcnt vmcnt(6)
	v_mov_b32_e32 v55, v25
	v_mov_b32_e32 v53, v24
	v_pk_mul_f32 v[54:55], v[54:55], v[54:55]
	v_mul_f32_e32 v48, 0x45800000, v52
	v_cndmask_b32_e32 v48, v52, v48, vcc
	v_mov_b32_e32 v52, v28
	v_pk_fma_f32 v[52:53], v[52:53], v[52:53], v[54:55]
	v_mov_b32_e32 v54, v30
	v_mov_b32_e32 v55, v26
	v_pk_fma_f32 v[52:53], v[54:55], v[54:55], v[52:53]
	v_mov_b32_e32 v54, v31
	v_mov_b32_e32 v55, v27
	s_waitcnt vmcnt(5)
	v_mov_b32_e32 v56, v21
	s_waitcnt vmcnt(4)
	v_mov_b32_e32 v57, v17
	v_pk_fma_f32 v[52:53], v[54:55], v[54:55], v[52:53]
	v_mov_b32_e32 v54, v20
	v_mov_b32_e32 v55, v16
	v_pk_mul_f32 v[56:57], v[56:57], v[56:57]
	v_add_f32_e32 v49, v52, v53
	v_pk_fma_f32 v[54:55], v[54:55], v[54:55], v[56:57]
	v_mov_b32_e32 v56, v22
	v_mov_b32_e32 v57, v18
	v_pk_fma_f32 v[54:55], v[56:57], v[56:57], v[54:55]
	v_mov_b32_e32 v56, v23
	v_mov_b32_e32 v57, v19
	v_pk_fma_f32 v[54:55], v[56:57], v[56:57], v[54:55]
	v_lshlrev_b64 v[50:51], 11, v[108:109]
	v_add_f32_e32 v49, v49, v54
	v_add_f32_e32 v49, v49, v55
	ds_bpermute_b32 v52, v225, v49
	v_pk_mul_f32 v[44:45], v[44:45], v[48:49] op_sel_hi:[1,0]
	v_pk_mul_f32 v[46:47], v[46:47], v[48:49] op_sel_hi:[1,0]
	v_pk_fma_f32 v[44:45], v[98:99], v[44:45], v[8:9]
	v_lshl_add_u64 v[50:51], v[100:101], 0, v[50:51]
	s_waitcnt lgkmcnt(0)
	v_add_f32_e32 v49, v49, v52
	ds_bpermute_b32 v54, v226, v49
	v_pk_mul_f32 v[40:41], v[40:41], v[48:49] op_sel_hi:[1,0]
	v_pk_mul_f32 v[42:43], v[42:43], v[48:49] op_sel_hi:[1,0]
	v_pk_fma_f32 v[46:47], v[96:97], v[46:47], v[10:11]
	v_pk_fma_f32 v[52:53], v[92:93], v[42:43], v[2:3]
	s_waitcnt lgkmcnt(0)
	v_add_f32_e32 v49, v49, v54
	ds_bpermute_b32 v54, v227, v49
	v_pk_fma_f32 v[42:43], v[94:95], v[40:41], v[0:1]
	v_cvt_pk_bf16_f32 v40, v44, v45
	v_cvt_pk_bf16_f32 v41, v46, v47
	v_pk_mul_f32 v[36:37], v[36:37], v[48:49] op_sel_hi:[1,0]
	s_waitcnt lgkmcnt(0)
	v_add_f32_e32 v44, v49, v54
	ds_bpermute_b32 v45, v228, v44
	v_cvt_pk_bf16_f32 v42, v42, v43
	v_cvt_pk_bf16_f32 v43, v52, v53
	global_store_dwordx4 v[50:51], v[40:43], off sc1
	v_pk_fma_f32 v[36:37], v[90:91], v[36:37], v[12:13]
	v_pk_mul_f32 v[32:33], v[32:33], v[48:49] op_sel_hi:[1,0]
	s_waitcnt lgkmcnt(0)
	v_add_f32_e32 v40, v44, v45
	ds_bpermute_b32 v41, v229, v40
	v_pk_mul_f32 v[34:35], v[34:35], v[48:49] op_sel_hi:[1,0]
	v_pk_mul_f32 v[38:39], v[38:39], v[48:49] op_sel_hi:[1,0]
	v_ashrrev_i32_e32 v111, 31, v110
	v_pk_fma_f32 v[38:39], v[88:89], v[38:39], v[14:15]
	s_waitcnt lgkmcnt(0)
	v_add_f32_e32 v42, v40, v41
	ds_bpermute_b32 v43, v230, v42
	v_pk_fma_f32 v[40:41], v[84:85], v[34:35], v[6:7]
	v_pk_fma_f32 v[34:35], v[86:87], v[32:33], v[4:5]
	v_cvt_pk_bf16_f32 v32, v36, v37
	v_cvt_pk_bf16_f32 v33, v38, v39
	s_waitcnt lgkmcnt(0)
; __device__ __forceinline__ void st_bf16x8(bf16_t* p, const f32x4 a, const f32x4 b) { uint4 o; o.x = cvt_pk_bf16(a[0], a[1]); o.y = cvt_pk_bf16(a[2], a[3]); o.z = cvt_pk_bf16(b[0], b[1]); o.w = cvt_pk_bf16(b[2], b[3]); *(uint4*)p = o; }
; __device__ __forceinline__ void p1_prompt_rows(const Params& p) {
;     ...
;     for (int trip = 0; trip < 2; ++trip) { const int rowb = gw * 8 + trip * 4;
;         f32x4 v[4][4];
; #pragma unroll
;         for (int q = 0; q < 4; ++q)
; #pragma unroll
;             for (int i = 0; i < 4; ++i) v[q][i] = *(const f32x4*)(p.x_prompt + (size_t)(rowb + q) * DM + (i >> 1) * 512 + lane * 8 + (i & 1) * 4);
;         __builtin_amdgcn_sched_barrier(0);
; #pragma unroll
;         for (int q = 0; q < 4; ++q) { float ss = 0.f;
; #pragma unroll
;             for (int i = 0; i < 4; ++i) ss += v[q][i][0] * v[q][i][0] + v[q][i][1] * v[q][i][1] + v[q][i][2] * v[q][i][2] + v[q][i][3] * v[q][i][3];
; #pragma unroll
;             for (int o = 1; o < 64; o <<= 1) ss += __shfl_xor(ss, o);
;             const float rs = rsqrtf(ss * (1.f / DM) + EPS);
; #pragma unroll
;             for (int h = 0; h < 2; ++h) st_bf16x8(H + (size_t)(rowb + q) * DM + h * 512 + lane * 8, v[q][2 * h] * rs * gs[2 * h] + sh[2 * h], v[q][2 * h + 1] * rs * gs[2 * h + 1] + sh[2 * h + 1]); }
	v_add_f32_e32 v36, v42, v43
	v_fmamk_f32 v36, v36, 0x3a800000, v82
	v_mul_f32_e32 v37, 0x4b800000, v36
	v_cmp_gt_f32_e32 vcc, s15, v36
	v_cvt_pk_bf16_f32 v34, v34, v35
	v_cvt_pk_bf16_f32 v35, v40, v41
	global_store_dwordx4 v[50:51], v[32:35], off offset:1024 sc1
	v_or_b32_e32 v112, 5, v102
	v_cndmask_b32_e32 v36, v36, v37, vcc
	v_rsq_f32_e32 v36, v36
	v_lshlrev_b64 v[34:35], 11, v[106:107]
	v_lshl_add_u64 v[34:35], v[100:101], 0, v[34:35]
	v_ashrrev_i32_e32 v113, 31, v112
	v_mul_f32_e32 v32, 0x45800000, v36
	v_cndmask_b32_e32 v32, v36, v32, vcc
	v_pk_mul_f32 v[28:29], v[28:29], v[32:33] op_sel_hi:[1,0]
	v_pk_mul_f32 v[30:31], v[30:31], v[32:33] op_sel_hi:[1,0]
	v_pk_mul_f32 v[24:25], v[24:25], v[32:33] op_sel_hi:[1,0]
	v_pk_mul_f32 v[26:27], v[26:27], v[32:33] op_sel_hi:[1,0]
	v_pk_fma_f32 v[30:31], v[96:97], v[30:31], v[10:11]
	v_pk_fma_f32 v[28:29], v[98:99], v[28:29], v[8:9]
	v_pk_fma_f32 v[36:37], v[92:93], v[26:27], v[2:3]
	v_pk_fma_f32 v[26:27], v[94:95], v[24:25], v[0:1]
	v_cvt_pk_bf16_f32 v24, v28, v29
	v_cvt_pk_bf16_f32 v25, v30, v31
	v_pk_mul_f32 v[20:21], v[20:21], v[32:33] op_sel_hi:[1,0]
	v_pk_mul_f32 v[22:23], v[22:23], v[32:33] op_sel_hi:[1,0]
	v_pk_mul_f32 v[16:17], v[16:17], v[32:33] op_sel_hi:[1,0]
	v_pk_mul_f32 v[18:19], v[18:19], v[32:33] op_sel_hi:[1,0]
	v_cvt_pk_bf16_f32 v26, v26, v27
	v_cvt_pk_bf16_f32 v27, v36, v37
	global_store_dwordx4 v[34:35], v[24:27], off sc1
	v_pk_fma_f32 v[22:23], v[88:89], v[22:23], v[14:15]
	v_pk_fma_f32 v[20:21], v[90:91], v[20:21], v[12:13]
	v_pk_fma_f32 v[24:25], v[84:85], v[18:19], v[6:7]
	v_pk_fma_f32 v[18:19], v[86:87], v[16:17], v[4:5]
	v_cvt_pk_bf16_f32 v16, v20, v21
	v_cvt_pk_bf16_f32 v17, v22, v23
	v_or_b32_e32 v66, 6, v102
	v_cvt_pk_bf16_f32 v18, v18, v19
	v_cvt_pk_bf16_f32 v19, v24, v25
	global_store_dwordx4 v[34:35], v[16:19], off offset:1024 sc1
	v_ashrrev_i32_e32 v67, 31, v66
	v_or_b32_e32 v64, 7, v102
	v_lshlrev_b64 v[16:17], 12, v[110:111]
	v_lshl_add_u64 v[16:17], v[104:105], 0, v[16:17]
	global_load_dwordx4 v[68:71], v[16:17], off nt
	global_load_dwordx4 v[72:75], v[16:17], off offset:16 nt
	global_load_dwordx4 v[76:79], v[16:17], off offset:2048 nt
	global_load_dwordx4 v[106:109], v[16:17], off offset:2064 nt
	v_lshlrev_b64 v[16:17], 12, v[112:113]
	v_lshl_add_u64 v[16:17], v[104:105], 0, v[16:17]
	global_load_dwordx4 v[60:63], v[16:17], off nt
	global_load_dwordx4 v[56:59], v[16:17], off offset:16 nt
	global_load_dwordx4 v[52:55], v[16:17], off offset:2048 nt
	global_load_dwordx4 v[48:51], v[16:17], off offset:2064 nt
	v_lshlrev_b64 v[16:17], 12, v[66:67]
	v_lshl_add_u64 v[16:17], v[104:105], 0, v[16:17]
	v_ashrrev_i32_e32 v65, 31, v64
	global_load_dwordx4 v[44:47], v[16:17], off nt
	global_load_dwordx4 v[40:43], v[16:17], off offset:16 nt
	global_load_dwordx4 v[36:39], v[16:17], off offset:2048 nt
	global_load_dwordx4 v[32:35], v[16:17], off offset:2064 nt
	v_lshlrev_b64 v[16:17], 12, v[64:65]
	v_lshl_add_u64 v[16:17], v[104:105], 0, v[16:17]
	global_load_dwordx4 v[28:31], v[16:17], off nt
	global_load_dwordx4 v[24:27], v[16:17], off offset:16 nt
	global_load_dwordx4 v[20:23], v[16:17], off offset:2048 nt
	s_nop 0
	global_load_dwordx4 v[16:19], v[16:17], off offset:2064 nt
	s_waitcnt vmcnt(15)
	v_mov_b32_e32 v104, v69
	s_waitcnt vmcnt(14)
	v_mov_b32_e32 v105, v73
	v_mov_b32_e32 v102, v68
	v_mov_b32_e32 v103, v72
	v_pk_mul_f32 v[104:105], v[104:105], v[104:105]
	s_waitcnt vmcnt(13)
	v_mov_b32_e32 v114, v77
	v_pk_fma_f32 v[102:103], v[102:103], v[102:103], v[104:105]
	v_mov_b32_e32 v104, v70
	v_mov_b32_e32 v105, v74
	v_pk_fma_f32 v[102:103], v[104:105], v[104:105], v[102:103]
	v_mov_b32_e32 v104, v71
	v_mov_b32_e32 v105, v75
	s_waitcnt vmcnt(12)
	v_mov_b32_e32 v115, v107
	v_pk_fma_f32 v[102:103], v[104:105], v[104:105], v[102:103]
	v_mov_b32_e32 v104, v76
	v_mov_b32_e32 v105, v106
	v_pk_mul_f32 v[114:115], v[114:115], v[114:115]
	v_add_f32_e32 v80, v102, v103
	v_pk_fma_f32 v[104:105], v[104:105], v[104:105], v[114:115]
	v_mov_b32_e32 v114, v78
	v_mov_b32_e32 v115, v108
	v_pk_fma_f32 v[104:105], v[114:115], v[114:115], v[104:105]
	v_mov_b32_e32 v114, v79
	v_mov_b32_e32 v115, v109
	v_pk_fma_f32 v[104:105], v[114:115], v[114:115], v[104:105]
	v_lshlrev_b64 v[102:103], 11, v[110:111]
	v_add_f32_e32 v80, v80, v104
	v_add_f32_e32 v80, v80, v105
	ds_bpermute_b32 v83, v225, v80
	s_waitcnt vmcnt(11)
	v_mov_b32_e32 v110, v61
	s_waitcnt vmcnt(10)
	v_mov_b32_e32 v111, v57
	v_mov_b32_e32 v104, v60
	v_mov_b32_e32 v105, v56
	s_waitcnt lgkmcnt(0)
	v_add_f32_e32 v80, v80, v83
	ds_bpermute_b32 v83, v226, v80
	v_pk_mul_f32 v[110:111], v[110:111], v[110:111]
	s_waitcnt vmcnt(9)
	v_mov_b32_e32 v114, v53
	v_pk_fma_f32 v[104:105], v[104:105], v[104:105], v[110:111]
	v_mov_b32_e32 v110, v62
	s_waitcnt lgkmcnt(0)
	v_add_f32_e32 v80, v80, v83
	ds_bpermute_b32 v83, v227, v80
	v_mov_b32_e32 v111, v58
	v_pk_fma_f32 v[104:105], v[110:111], v[110:111], v[104:105]
	v_mov_b32_e32 v110, v63
	v_mov_b32_e32 v111, v59
	s_waitcnt lgkmcnt(0)
	v_add_f32_e32 v80, v80, v83
	ds_bpermute_b32 v83, v228, v80
	s_waitcnt vmcnt(8)
	v_mov_b32_e32 v115, v49
	v_pk_fma_f32 v[104:105], v[110:111], v[110:111], v[104:105]
	v_mov_b32_e32 v110, v52
	v_mov_b32_e32 v111, v48
	s_waitcnt lgkmcnt(0)
	v_add_f32_e32 v80, v80, v83
	ds_bpermute_b32 v83, v229, v80
	v_pk_mul_f32 v[114:115], v[114:115], v[114:115]
	v_lshl_add_u64 v[102:103], v[100:101], 0, v[102:103]
	v_pk_fma_f32 v[110:111], v[110:111], v[110:111], v[114:115]
	v_mov_b32_e32 v114, v54
	s_waitcnt lgkmcnt(0)
	v_add_f32_e32 v80, v80, v83
	ds_bpermute_b32 v83, v230, v80
	v_mov_b32_e32 v115, v50
	v_pk_fma_f32 v[110:111], v[114:115], v[114:115], v[110:111]
	v_mov_b32_e32 v114, v55
	v_mov_b32_e32 v115, v51
	s_waitcnt lgkmcnt(0)
; __device__ __forceinline__ void st_bf16x8(bf16_t* p, const f32x4 a, const f32x4 b) { uint4 o; o.x = cvt_pk_bf16(a[0], a[1]); o.y = cvt_pk_bf16(a[2], a[3]); o.z = cvt_pk_bf16(b[0], b[1]); o.w = cvt_pk_bf16(b[2], b[3]); *(uint4*)p = o; }
; __device__ __forceinline__ void p1_prompt_rows(const Params& p) {
;     ...
; #pragma unroll
;         for (int q = 0; q < 4; ++q) { float ss = 0.f;
; #pragma unroll
;             for (int i = 0; i < 4; ++i) ss += v[q][i][0] * v[q][i][0] + v[q][i][1] * v[q][i][1] + v[q][i][2] * v[q][i][2] + v[q][i][3] * v[q][i][3];
; #pragma unroll
;             for (int o = 1; o < 64; o <<= 1) ss += __shfl_xor(ss, o);
;             const float rs = rsqrtf(ss * (1.f / DM) + EPS);
; #pragma unroll
;             for (int h = 0; h < 2; ++h) st_bf16x8(H + (size_t)(rowb + q) * DM + h * 512 + lane * 8, v[q][2 * h] * rs * gs[2 * h] + sh[2 * h], v[q][2 * h + 1] * rs * gs[2 * h + 1] + sh[2 * h + 1]); }
	v_add_f32_e32 v80, v80, v83
	v_fmamk_f32 v80, v80, 0x3a800000, v82
	v_mul_f32_e32 v83, 0x4b800000, v80
	v_cmp_gt_f32_e32 vcc, s15, v80
	v_pk_fma_f32 v[110:111], v[114:115], v[114:115], v[110:111]
	s_movk_i32 s33, 0x4080
	v_cndmask_b32_e32 v80, v80, v83, vcc
	v_rsq_f32_e32 v80, v80
	s_nop 0
	v_mul_f32_e32 v83, 0x45800000, v80
	v_cndmask_b32_e32 v80, v80, v83, vcc
	v_add_f32_e32 v83, v104, v105
	v_add_f32_e32 v83, v83, v110
	v_add_f32_e32 v83, v83, v111
	ds_bpermute_b32 v104, v225, v83
	v_pk_mul_f32 v[68:69], v[68:69], v[80:81] op_sel_hi:[1,0]
	v_pk_mul_f32 v[70:71], v[70:71], v[80:81] op_sel_hi:[1,0]
	v_pk_mul_f32 v[72:73], v[72:73], v[80:81] op_sel_hi:[1,0]
	v_pk_fma_f32 v[70:71], v[96:97], v[70:71], v[10:11]
	s_waitcnt lgkmcnt(0)
	v_add_f32_e32 v83, v83, v104
	ds_bpermute_b32 v104, v226, v83
	v_pk_fma_f32 v[68:69], v[98:99], v[68:69], v[8:9]
	v_pk_fma_f32 v[72:73], v[94:95], v[72:73], v[0:1]
	v_cvt_pk_bf16_f32 v68, v68, v69
	v_cvt_pk_bf16_f32 v69, v70, v71
	s_waitcnt lgkmcnt(0)
	v_add_f32_e32 v83, v83, v104
	ds_bpermute_b32 v104, v227, v83
	v_cvt_pk_bf16_f32 v70, v72, v73
	v_pk_mul_f32 v[74:75], v[74:75], v[80:81] op_sel_hi:[1,0]
	s_waitcnt lgkmcnt(0)
	v_add_f32_e32 v72, v83, v104
	ds_bpermute_b32 v73, v228, v72
	v_pk_fma_f32 v[74:75], v[92:93], v[74:75], v[2:3]
	s_nop 0
	v_cvt_pk_bf16_f32 v71, v74, v75
	global_store_dwordx4 v[102:103], v[68:71], off sc1
	v_pk_mul_f32 v[74:75], v[108:109], v[80:81] op_sel_hi:[1,0]
	s_nop 0
	v_pk_mul_f32 v[68:69], v[76:77], v[80:81] op_sel_hi:[1,0]
	s_waitcnt lgkmcnt(0)
	v_add_f32_e32 v76, v72, v73
	ds_bpermute_b32 v77, v229, v76
	v_pk_mul_f32 v[70:71], v[78:79], v[80:81] op_sel_hi:[1,0]
	v_pk_fma_f32 v[68:69], v[90:91], v[68:69], v[12:13]
	v_pk_fma_f32 v[70:71], v[88:89], v[70:71], v[14:15]
	v_cvt_pk_bf16_f32 v68, v68, v69
	s_waitcnt lgkmcnt(0)
	v_add_f32_e32 v76, v76, v77
	ds_bpermute_b32 v77, v230, v76
	v_cvt_pk_bf16_f32 v69, v70, v71
	v_pk_mul_f32 v[72:73], v[106:107], v[80:81] op_sel_hi:[1,0]
	v_pk_fma_f32 v[74:75], v[84:85], v[74:75], v[6:7]
	v_pk_fma_f32 v[72:73], v[86:87], v[72:73], v[4:5]
	s_waitcnt lgkmcnt(0)
	v_add_f32_e32 v70, v76, v77
	v_fmamk_f32 v70, v70, 0x3a800000, v82
	v_mul_f32_e32 v71, 0x4b800000, v70
	v_cmp_gt_f32_e32 vcc, s15, v70
	s_waitcnt vmcnt(5)
	v_mov_b32_e32 v77, v33
	v_cndmask_b32_e32 v70, v70, v71, vcc
	v_rsq_f32_e32 v76, v70
	v_cvt_pk_bf16_f32 v71, v74, v75
	v_mov_b32_e32 v74, v45
	v_mov_b32_e32 v75, v41
	v_cvt_pk_bf16_f32 v70, v72, v73
	v_mov_b32_e32 v72, v44
	v_mov_b32_e32 v73, v40
	v_pk_mul_f32 v[74:75], v[74:75], v[74:75]
	global_store_dwordx4 v[102:103], v[68:71], off offset:1024 sc1
	v_pk_fma_f32 v[72:73], v[72:73], v[72:73], v[74:75]
	v_mov_b32_e32 v74, v46
	v_mul_f32_e32 v68, 0x45800000, v76
	v_mov_b32_e32 v75, v42
	v_cndmask_b32_e32 v68, v76, v68, vcc
	v_pk_fma_f32 v[72:73], v[74:75], v[74:75], v[72:73]
	v_mov_b32_e32 v74, v47
	v_mov_b32_e32 v75, v43
	v_mov_b32_e32 v76, v37
	v_pk_fma_f32 v[72:73], v[74:75], v[74:75], v[72:73]
	v_mov_b32_e32 v74, v36
	v_mov_b32_e32 v75, v32
	v_pk_mul_f32 v[76:77], v[76:77], v[76:77]
	v_add_f32_e32 v69, v72, v73
	v_pk_fma_f32 v[74:75], v[74:75], v[74:75], v[76:77]
	v_mov_b32_e32 v76, v38
	v_mov_b32_e32 v77, v34
	v_pk_fma_f32 v[74:75], v[76:77], v[76:77], v[74:75]
	v_mov_b32_e32 v76, v39
	v_mov_b32_e32 v77, v35
	v_pk_fma_f32 v[74:75], v[76:77], v[76:77], v[74:75]
	v_lshlrev_b64 v[70:71], 11, v[112:113]
	v_add_f32_e32 v69, v69, v74
	v_add_f32_e32 v69, v69, v75
	ds_bpermute_b32 v72, v225, v69
	v_pk_mul_f32 v[60:61], v[60:61], v[68:69] op_sel_hi:[1,0]
	v_pk_mul_f32 v[62:63], v[62:63], v[68:69] op_sel_hi:[1,0]
	v_pk_fma_f32 v[60:61], v[98:99], v[60:61], v[8:9]
	v_lshl_add_u64 v[70:71], v[100:101], 0, v[70:71]
	s_waitcnt lgkmcnt(0)
	v_add_f32_e32 v69, v69, v72
	ds_bpermute_b32 v74, v226, v69
	v_pk_mul_f32 v[56:57], v[56:57], v[68:69] op_sel_hi:[1,0]
	v_pk_mul_f32 v[58:59], v[58:59], v[68:69] op_sel_hi:[1,0]
	v_pk_fma_f32 v[62:63], v[96:97], v[62:63], v[10:11]
	v_pk_fma_f32 v[72:73], v[92:93], v[58:59], v[2:3]
	s_waitcnt lgkmcnt(0)
	v_add_f32_e32 v69, v69, v74
	ds_bpermute_b32 v74, v227, v69
	v_pk_fma_f32 v[58:59], v[94:95], v[56:57], v[0:1]
	v_cvt_pk_bf16_f32 v56, v60, v61
	v_cvt_pk_bf16_f32 v57, v62, v63
	v_pk_mul_f32 v[52:53], v[52:53], v[68:69] op_sel_hi:[1,0]
	s_waitcnt lgkmcnt(0)
	v_add_f32_e32 v60, v69, v74
	ds_bpermute_b32 v61, v228, v60
	v_cvt_pk_bf16_f32 v58, v58, v59
	v_cvt_pk_bf16_f32 v59, v72, v73
	global_store_dwordx4 v[70:71], v[56:59], off sc1
	v_pk_fma_f32 v[52:53], v[90:91], v[52:53], v[12:13]
	v_pk_mul_f32 v[48:49], v[48:49], v[68:69] op_sel_hi:[1,0]
	s_waitcnt lgkmcnt(0)
	v_add_f32_e32 v56, v60, v61
	ds_bpermute_b32 v57, v229, v56
	v_pk_mul_f32 v[50:51], v[50:51], v[68:69] op_sel_hi:[1,0]
	v_pk_mul_f32 v[54:55], v[54:55], v[68:69] op_sel_hi:[1,0]
	s_waitcnt lgkmcnt(0)
	v_add_f32_e32 v58, v56, v57
	ds_bpermute_b32 v59, v230, v58
	v_pk_fma_f32 v[56:57], v[84:85], v[50:51], v[6:7]
	v_pk_fma_f32 v[50:51], v[86:87], v[48:49], v[4:5]
	v_cvt_pk_bf16_f32 v48, v52, v53
	v_pk_fma_f32 v[54:55], v[88:89], v[54:55], v[14:15]
	s_waitcnt lgkmcnt(0)
	v_add_f32_e32 v52, v58, v59
	v_fmamk_f32 v52, v52, 0x3a800000, v82
	v_mul_f32_e32 v53, 0x4b800000, v52
	v_cmp_gt_f32_e32 vcc, s15, v52
	v_cvt_pk_bf16_f32 v49, v54, v55
	v_cvt_pk_bf16_f32 v50, v50, v51
	v_cvt_pk_bf16_f32 v51, v56, v57
	global_store_dwordx4 v[70:71], v[48:51], off offset:1024 sc1
	s_waitcnt vmcnt(7)
	v_mov_b32_e32 v54, v29
	v_cndmask_b32_e32 v52, v52, v53, vcc
	v_rsq_f32_e32 v52, v52
	s_waitcnt vmcnt(6)
; __device__ __forceinline__ int fresh_tid() { int t = threadIdx.x; asm volatile("" : "+v"(t)); return t; }
; __device__ __forceinline__ void st_bf16x8(bf16_t* p, const f32x4 a, const f32x4 b) { uint4 o; o.x = cvt_pk_bf16(a[0], a[1]); o.y = cvt_pk_bf16(a[2], a[3]); o.z = cvt_pk_bf16(b[0], b[1]); o.w = cvt_pk_bf16(b[2], b[3]); *(uint4*)p = o; }
;     const int tid = fresh_tid(), lane = tid & 63, gw = blockIdx.x * 8 + (tid >> 6), nw = (nblk ? nblk : (int)gridDim.x) * 8;
;     const float* mod = (const float*)(p.ws + WS_MOD); bf16_t* H = (bf16_t*)(p.ws + WS_H);
;     f32x4 gv[4];
; #pragma unroll
;     for (int i = 0; i < 4; ++i) gv[i] = *(const f32x4*)(g + (i >> 1) * 512 + lane * 8 + (i & 1) * 4);
;     for (int rowb = r0 + gw; rowb < r1; rowb += 4 * nw) {
;         f32x4 v[4][4];
; #pragma unroll
;         for (int q = 0; q < 4; ++q) { const int row = rowb + q * nw;
;             if (row < r1) { const float* src = from_out ? p.out + (size_t)row * DM : (row < NP ? p.x_prompt + (size_t)row * DM : p.x_sample + (size_t)(row - NP) * DM);
; __device__ __forceinline__ void p1_prompt_rows(const Params& p) {
;     ...
;         for (int q = 0; q < 4; ++q) { float ss = 0.f;
; #pragma unroll
;             for (int i = 0; i < 4; ++i) ss += v[q][i][0] * v[q][i][0] + v[q][i][1] * v[q][i][1] + v[q][i][2] * v[q][i][2] + v[q][i][3] * v[q][i][3];
; #pragma unroll
;             for (int o = 1; o < 64; o <<= 1) ss += __shfl_xor(ss, o);
;             const float rs = rsqrtf(ss * (1.f / DM) + EPS);
; #pragma unroll
;             for (int h = 0; h < 2; ++h) st_bf16x8(H + (size_t)(rowb + q) * DM + h * 512 + lane * 8, v[q][2 * h] * rs * gs[2 * h] + sh[2 * h], v[q][2 * h + 1] * rs * gs[2 * h + 1] + sh[2 * h + 1]); }
	v_mov_b32_e32 v55, v25
	v_mov_b32_e32 v53, v24
	v_pk_mul_f32 v[54:55], v[54:55], v[54:55]
	v_mul_f32_e32 v48, 0x45800000, v52
	v_cndmask_b32_e32 v48, v52, v48, vcc
	v_mov_b32_e32 v52, v28
	v_pk_fma_f32 v[52:53], v[52:53], v[52:53], v[54:55]
	v_mov_b32_e32 v54, v30
	v_mov_b32_e32 v55, v26
	v_pk_fma_f32 v[52:53], v[54:55], v[54:55], v[52:53]
	v_mov_b32_e32 v54, v31
	v_mov_b32_e32 v55, v27
	s_waitcnt vmcnt(5)
	v_mov_b32_e32 v56, v21
	s_waitcnt vmcnt(4)
	v_mov_b32_e32 v57, v17
	v_pk_fma_f32 v[52:53], v[54:55], v[54:55], v[52:53]
	v_mov_b32_e32 v54, v20
	v_mov_b32_e32 v55, v16
	v_pk_mul_f32 v[56:57], v[56:57], v[56:57]
	v_add_f32_e32 v49, v52, v53
	v_pk_fma_f32 v[54:55], v[54:55], v[54:55], v[56:57]
	v_mov_b32_e32 v56, v22
	v_mov_b32_e32 v57, v18
	v_pk_fma_f32 v[54:55], v[56:57], v[56:57], v[54:55]
	v_mov_b32_e32 v56, v23
	v_mov_b32_e32 v57, v19
	v_pk_fma_f32 v[54:55], v[56:57], v[56:57], v[54:55]
	v_lshlrev_b64 v[50:51], 11, v[66:67]
	v_add_f32_e32 v49, v49, v54
	v_add_f32_e32 v49, v49, v55
	ds_bpermute_b32 v52, v225, v49
	v_pk_mul_f32 v[44:45], v[44:45], v[48:49] op_sel_hi:[1,0]
	v_pk_mul_f32 v[46:47], v[46:47], v[48:49] op_sel_hi:[1,0]
	v_pk_fma_f32 v[44:45], v[98:99], v[44:45], v[8:9]
	v_lshl_add_u64 v[50:51], v[100:101], 0, v[50:51]
	s_waitcnt lgkmcnt(0)
	v_add_f32_e32 v49, v49, v52
	ds_bpermute_b32 v54, v226, v49
	v_pk_mul_f32 v[40:41], v[40:41], v[48:49] op_sel_hi:[1,0]
	v_pk_mul_f32 v[42:43], v[42:43], v[48:49] op_sel_hi:[1,0]
	v_pk_fma_f32 v[46:47], v[96:97], v[46:47], v[10:11]
	v_pk_fma_f32 v[52:53], v[92:93], v[42:43], v[2:3]
	s_waitcnt lgkmcnt(0)
	v_add_f32_e32 v49, v49, v54
	ds_bpermute_b32 v54, v227, v49
	v_pk_fma_f32 v[42:43], v[94:95], v[40:41], v[0:1]
	v_cvt_pk_bf16_f32 v40, v44, v45
	v_cvt_pk_bf16_f32 v41, v46, v47
	v_pk_mul_f32 v[36:37], v[36:37], v[48:49] op_sel_hi:[1,0]
	s_waitcnt lgkmcnt(0)
	v_add_f32_e32 v44, v49, v54
	ds_bpermute_b32 v45, v228, v44
	v_cvt_pk_bf16_f32 v42, v42, v43
	v_cvt_pk_bf16_f32 v43, v52, v53
	global_store_dwordx4 v[50:51], v[40:43], off sc1
	v_pk_fma_f32 v[36:37], v[90:91], v[36:37], v[12:13]
	v_pk_mul_f32 v[32:33], v[32:33], v[48:49] op_sel_hi:[1,0]
	s_waitcnt lgkmcnt(0)
	v_add_f32_e32 v40, v44, v45
	ds_bpermute_b32 v41, v229, v40
	v_pk_mul_f32 v[34:35], v[34:35], v[48:49] op_sel_hi:[1,0]
	v_pk_mul_f32 v[38:39], v[38:39], v[48:49] op_sel_hi:[1,0]
	s_waitcnt lgkmcnt(0)
	v_add_f32_e32 v42, v40, v41
	ds_bpermute_b32 v43, v230, v42
	v_pk_fma_f32 v[40:41], v[84:85], v[34:35], v[6:7]
	v_pk_fma_f32 v[34:35], v[86:87], v[32:33], v[4:5]
	v_cvt_pk_bf16_f32 v32, v36, v37
	v_pk_fma_f32 v[38:39], v[88:89], v[38:39], v[14:15]
	s_waitcnt lgkmcnt(0)
	v_add_f32_e32 v36, v42, v43
	v_fmamk_f32 v36, v36, 0x3a800000, v82
	v_mul_f32_e32 v37, 0x4b800000, v36
	v_cmp_gt_f32_e32 vcc, s15, v36
	v_cvt_pk_bf16_f32 v33, v38, v39
	v_cvt_pk_bf16_f32 v34, v34, v35
	v_cvt_pk_bf16_f32 v35, v40, v41
	global_store_dwordx4 v[50:51], v[32:35], off offset:1024 sc1
	s_nop 0
	v_cndmask_b32_e32 v36, v36, v37, vcc
	v_rsq_f32_e32 v36, v36
	v_lshlrev_b64 v[34:35], 11, v[64:65]
	v_lshl_add_u64 v[34:35], v[100:101], 0, v[34:35]
	v_mul_f32_e32 v32, 0x45800000, v36
	v_cndmask_b32_e32 v32, v36, v32, vcc
	v_pk_mul_f32 v[24:25], v[24:25], v[32:33] op_sel_hi:[1,0]
	v_pk_mul_f32 v[26:27], v[26:27], v[32:33] op_sel_hi:[1,0]
	v_pk_mul_f32 v[28:29], v[28:29], v[32:33] op_sel_hi:[1,0]
	v_pk_mul_f32 v[30:31], v[30:31], v[32:33] op_sel_hi:[1,0]
	v_pk_fma_f32 v[26:27], v[92:93], v[26:27], v[2:3]
	v_pk_fma_f32 v[2:3], v[94:95], v[24:25], v[0:1]
	v_pk_fma_f32 v[10:11], v[96:97], v[30:31], v[10:11]
	v_pk_fma_f32 v[8:9], v[98:99], v[28:29], v[8:9]
	v_cvt_pk_bf16_f32 v1, v10, v11
	v_cvt_pk_bf16_f32 v2, v2, v3
	v_cvt_pk_bf16_f32 v3, v26, v27
	v_pk_mul_f32 v[10:11], v[18:19], v[32:33] op_sel_hi:[1,0]
	v_cvt_pk_bf16_f32 v0, v8, v9
	global_store_dwordx4 v[34:35], v[0:3], off sc1
	v_pk_mul_f32 v[8:9], v[16:17], v[32:33] op_sel_hi:[1,0]
	v_mov_b32_e32 v17, v224
	v_pk_mul_f32 v[0:1], v[20:21], v[32:33] op_sel_hi:[1,0]
	v_pk_mul_f32 v[2:3], v[22:23], v[32:33] op_sel_hi:[1,0]
	v_pk_fma_f32 v[0:1], v[90:91], v[0:1], v[12:13]
	v_pk_fma_f32 v[2:3], v[88:89], v[2:3], v[14:15]
	v_pk_fma_f32 v[6:7], v[84:85], v[10:11], v[6:7]
	v_pk_fma_f32 v[4:5], v[86:87], v[8:9], v[4:5]
	v_cvt_pk_bf16_f32 v0, v0, v1
	v_cvt_pk_bf16_f32 v1, v2, v3
	v_cvt_pk_bf16_f32 v3, v6, v7
	s_nop 0
	v_cvt_pk_bf16_f32 v2, v4, v5
	global_store_dwordx4 v[34:35], v[0:3], off offset:1024 sc1
	s_nop 0
	v_ashrrev_i32_e32 v16, 6, v17
	v_add_u32_e32 v64, s97, v16
	v_cmp_gt_i32_e32 vcc, s33, v64
	s_and_saveexec_b64 s[30:31], vcc
	s_cbranch_execz .LBB0_148
	v_lshlrev_b32_e32 v0, 3, v17
	v_and_b32_e32 v66, 0x1f8, v0
	v_lshlrev_b32_e32 v12, 2, v66
	global_load_dwordx4 v[0:3], v12, s[46:47] offset:16
	global_load_dwordx4 v[4:7], v12, s[46:47]
	global_load_dwordx4 v[8:11], v12, s[46:47] offset:2064
	s_nop 0
	global_load_dwordx4 v[12:15], v12, s[46:47] offset:2048
	s_add_i32 s0, s94, s95
	v_add_u32_e32 v16, s0, v16
	v_add_u32_e32 v72, 0x4000, v16
	v_and_b32_e32 v17, 63, v17
	v_ashrrev_i32_e32 v73, 31, v72
	s_lshl_b32 s46, s34, 5
	v_lshlrev_b32_e32 v70, 4, v17
	v_lshlrev_b64 v[16:17], 11, v[72:73]
	v_ashrrev_i32_e32 v65, 31, v64
	v_or_b32_e32 v18, 0x200, v66
	v_lshlrev_b32_e32 v80, 1, v66
	v_lshl_add_u64 v[74:75], s[58:59], 0, v[16:17]
	s_ashr_i32 s47, s46, 31
	v_lshlrev_b64 v[16:17], 11, v[64:65]
	v_lshl_add_u64 v[68:69], s[26:27], 0, v[80:81]
	s_lshl_b32 s60, s34, 4
	s_mul_i32 s61, s34, 24
	v_mov_b32_e32 v71, v81
	s_lshl_b64 s[48:49], s[46:47], 11
	v_lshl_add_u64 v[76:77], s[58:59], 0, v[16:17]
	s_mov_b64 s[50:51], 0
	s_mov_b32 s66, 0x1a70000
	v_lshlrev_b32_e32 v78, 2, v18
	s_movk_i32 s67, 0x407f
	s_mov_b64 s[52:53], 0
	v_mov_b32_e32 v67, v64
	s_branch .LBB0_136

; __device__ __forceinline__ unsigned xb_ld(unsigned* p)              { return __hip_atomic_load(p, __ATOMIC_RELAXED, __HIP_MEMORY_SCOPE_AGENT); }
; __device__ __forceinline__ unsigned xb_add(unsigned* p, unsigned v) { return __hip_atomic_fetch_add(p, v, __ATOMIC_RELAXED, __HIP_MEMORY_SCOPE_AGENT); }
; #define XB_SPIN(cond, bar) do { unsigned _sp = 0; while (cond) { __builtin_amdgcn_s_sleep(1); \
;     if ((++_sp & 255u) == 0u) { if (xb_ld(&(bar)[XB_TMO])) break; if (_sp > XB_SPIN_CAP) { atomicAdd(&(bar)[XB_TMO], 1u); break; } } } } while (0)
; __device__ __forceinline__ void xcd_barrier(const XcdBarrier& b) {
;     asm volatile("s_waitcnt vmcnt(0)" ::: "memory");
;     __syncthreads();
;     if (threadIdx.x == 0) {
;         unsigned* bar = b.bar;
;         __builtin_amdgcn_s_waitcnt(0);
;         unsigned nloc = b.st[0], nx = b.st[1];
;         if (nloc == 0u) { xcd_barrier_complete(bar, b.x, nloc, nx); b.st[0] = nloc; b.st[1] = nx; }
;         const unsigned old = xb_add(&bar[XB_XSUB(b.x)], 1u);
;         const unsigned gen = old / nloc;
;         if (old + 1u == (gen + 1u) * nloc) {
;             __builtin_amdgcn_fence(__ATOMIC_RELEASE, "agent");
;             asm volatile("s_waitcnt vmcnt(0)" ::: "memory");
;             const unsigned og = xb_add(&bar[XB_TOP], 1u);
;             const unsigned tg = og / nx;
;             asm volatile("buffer_inv sc1" ::: "memory");
;             if (og + 1u == (tg + 1u) * nx) xb_add(&bar[XB_TOPGEN], 1u);
;             else XB_SPIN(xb_ld(&bar[XB_TOPGEN]) == tg, bar);
;             xb_add(&bar[XB_XGEN(b.x)], 1u);
;             asm volatile("s_waitcnt vmcnt(0)" ::: "memory");
;         } else {
;             asm volatile("buffer_inv sc1" ::: "memory");
;             XB_SPIN(xb_ld(&bar[XB_XGEN(b.x)]) == gen, bar);
;             asm volatile("s_waitcnt vmcnt(0)" ::: "memory");
;         }
;     }
;     __syncthreads();
; }
.Lgb_body:
	v_mov_b32_e32 v0, 0
	s_waitcnt vmcnt(0) lgkmcnt(0)
	ds_read_b32 v2, v0
	ds_read_b32 v1, v0 offset:4
	s_getreg_b32 s75, hwreg(HW_REG_XCC_ID, 0, 4)
	s_and_b32 s75, s75, 15
	s_lshl_b32 s75, s75, 8
	s_add_u32 s76, s58, 0xc938000
	s_addc_u32 s77, s59, 0
	s_add_u32 s78, s76, s75
	s_addc_u32 s79, s77, 0
	v_mov_b32_e32 v3, 0x1000
	v_mov_b32_e32 v4, 1
	s_nop 3
	global_atomic_add v3, v3, v4, s[78:79] offset:1024 sc0
	s_waitcnt lgkmcnt(0)
	s_nop 0
	v_readfirstlane_b32 s80, v2
	v_readfirstlane_b32 s81, v1
	s_add_i32 s82, s73, 1
	s_mul_i32 s83, s73, s80
	s_waitcnt vmcnt(0)
	s_nop 0
	v_readfirstlane_b32 s84, v3
	s_add_i32 s84, s84, 1
	s_cmp_lg_u32 s84, s83
	s_cbranch_scc1 .Lgb_wait
	buffer_wbl2 sc1
	s_waitcnt vmcnt(0) lgkmcnt(0)
	v_mov_b32_e32 v3, 0x3000
	v_mov_b32_e32 v4, 1
	global_atomic_add v3, v3, v4, s[76:77] offset:1024 sc0
	buffer_inv sc1
	s_mul_i32 s85, s73, s81
	s_waitcnt vmcnt(0)
	s_nop 0
	v_readfirstlane_b32 s86, v3
	s_add_i32 s86, s86, 1
	s_cmp_lg_u32 s86, s85
	s_cbranch_scc1 .Lgb_leadwait
	v_mov_b32_e32 v3, 0x3000
	global_atomic_add v3, v4, s[76:77] offset:1280
	s_mov_b64 exec, 0xffff
	v_mbcnt_lo_u32_b32 v0, -1, 0
	v_lshlrev_b32_e32 v0, 8, v0
	v_add_u32_e32 v0, 0x2400, v0
	v_mov_b32_e32 v1, 1
	global_atomic_add v0, v1, s[76:77]
	s_mov_b64 exec, 1
	s_branch .Lgb_done

; __device__ __forceinline__ unsigned xb_ld(unsigned* p)              { return __hip_atomic_load(p, __ATOMIC_RELAXED, __HIP_MEMORY_SCOPE_AGENT); }
; __device__ __forceinline__ unsigned xb_add(unsigned* p, unsigned v) { return __hip_atomic_fetch_add(p, v, __ATOMIC_RELAXED, __HIP_MEMORY_SCOPE_AGENT); }
; #define XB_SPIN(cond, bar) do { unsigned _sp = 0; while (cond) { __builtin_amdgcn_s_sleep(1); \
;     if ((++_sp & 255u) == 0u) { if (xb_ld(&(bar)[XB_TMO])) break; if (_sp > XB_SPIN_CAP) { atomicAdd(&(bar)[XB_TMO], 1u); break; } } } } while (0)
; __device__ __forceinline__ void xcd_barrier(const XcdBarrier& b) {
;     ...
;             else XB_SPIN(xb_ld(&bar[XB_TOPGEN]) == tg, bar);
;             xb_add(&bar[XB_XGEN(b.x)], 1u);
;             asm volatile("s_waitcnt vmcnt(0)" ::: "memory");
;         } else {
;             asm volatile("buffer_inv sc1" ::: "memory");
;             XB_SPIN(xb_ld(&bar[XB_XGEN(b.x)]) == gen, bar);
;             asm volatile("s_waitcnt vmcnt(0)" ::: "memory");
.Lgb_loop:
	global_load_dword v1, v0, s[78:79] sc1
	s_waitcnt vmcnt(0)
	s_nop 0
	v_readfirstlane_b32 s88, v1
	s_cmp_ge_u32 s88, s73
	s_cbranch_scc1 .Lgb_done
	s_sleep 1
	s_add_i32 s87, s87, 1
	s_cmp_lt_u32 s87, 0x40000
	s_cbranch_scc1 .Lgb_loop
